# y-offload: RWKV consumers write per-lane partial y to LDS ring, loader waves do 16-lane reductions + YR stores; SGU one job per WG
# speedup vs baseline: 1.0168x; 1.0015x over previous
; #define LAS __attribute__((address_space(3)))
; #define GAS __attribute__((address_space(1)))
; __device__ __forceinline__ void sgu_job(LAS unsigned char* lds, const GAS float* Wh, const GAS float* sbias, const GAS float* VLN, GAS float* U, int m0, int h, int tid) {
;     LAS float* WL = (LAS float*)lds;
;     LAS float* VT = (LAS float*)(lds + 67584);
; #pragma unroll 2
;     for (int i0 = 0; i0 < 32; i0 += 16) { float tw[16], tv[16];
; #pragma unroll
;         for (int i = 0; i < 16; ++i) { const int idx = tid + 512 * (i0 + i), t = idx >> 7, s = idx & 127; tw[i] = Wh[idx]; tv[i] = VLN[(size_t)(m0 + t) * 512 + h * 128 + s]; }
; #pragma unroll
;         for (int i = 0; i < 16; ++i) { const int idx = tid + 512 * (i0 + i), t = idx >> 7, s = idx & 127; WL[t * 132 + s] = (s <= t) ? tw[i] : 0.f; VT[idx] = tv[i]; } }
; __device__ __forceinline__ void m2_phase(ArgP A, int layer, LAS unsigned char* lds, int tid, int lane, int wave, int bid, int G) {
;     ...
;     if (bid >= (G >> 1)) for (int job = bid - (G >> 1); job < 256; job += G - (G >> 1)) { const int b = job >> 6, n = (job >> 2) & 15, h = job & 3;
;         sgu_job(lds, A->in[26] + ((size_t)layer * 4 + h) * 128 * 128, A->in[27] + (layer * 4 + h) * 128, VLN, U, b * SEQ + n * 128, h, tid); }
.LBB0_618:
	s_cmp_le_i32 s74, s18
	s_cselect_b64 s[38:39], -1, 0
	s_and_b64 s[0:1], s[38:39], s[4:5]
	s_andn2_b64 vcc, exec, s[0:1]
	s_cbranch_vccnz .LBB0_709
	v_mov_b32_e32 v190, v195
	s_mov_b64 s[28:29], s[68:69]
	s_load_dwordx2 s[20:21], s[28:29], 0x138
	s_load_dwordx2 s[26:27], s[28:29], 0xe8
	v_readlane_b32 s0, v252, 60
	v_readlane_b32 s1, v252, 61
	v_readfirstlane_b32 s14, v190
	v_and_b32_e32 v236, 15, v190
	v_readlane_b32 s0, v254, 10
	s_waitcnt vmcnt(0)
	v_and_b32_e32 v2, 0x7f, v190
	v_readlane_b32 s1, v254, 11
	v_lshlrev_b32_e32 v16, 2, v2
	s_lshl_b32 s15, s0, 16
	s_lshl_b32 s22, s0, 9
	s_waitcnt lgkmcnt(0)
	v_lshl_add_u64 v[0:1], s[20:21], 0, v[16:17]
	s_mov_b64 s[0:1], 0x25700000
	v_lshl_add_u64 v[0:1], v[0:1], 0, s[0:1]
	v_add_u32_e32 v10, 0, v16
	v_add_u32_e32 v3, 0x200, v190
	v_add_u32_e32 v4, 0x400, v190
	v_add_u32_e32 v5, 0x600, v190
	v_add_u32_e32 v6, 0x800, v190
	v_add_u32_e32 v7, 0xa00, v190
	v_add_u32_e32 v16, 0x1600, v190
	v_add_u32_e32 v21, 0x1e00, v190
	v_readlane_b32 s1, v253, 49
	s_load_dwordx4 s[16:19], s[28:29], 0xd0
	v_ashrrev_i32_e32 v47, 7, v3
	v_ashrrev_i32_e32 v48, 7, v4
	v_ashrrev_i32_e32 v49, 7, v5
	v_ashrrev_i32_e32 v50, 7, v6
	v_ashrrev_i32_e32 v51, 7, v7
	v_add_u32_e32 v11, 0xc00, v190
	v_add_u32_e32 v12, 0xe00, v190
	v_add_u32_e32 v13, 0x1000, v190
	v_add_u32_e32 v14, 0x1200, v190
	v_add_u32_e32 v15, 0x1400, v190
	v_ashrrev_i32_e32 v57, 7, v16
	v_add_u32_e32 v18, 0x1800, v190
	v_add_u32_e32 v19, 0x1a00, v190
	v_add_u32_e32 v20, 0x1c00, v190
	v_ashrrev_i32_e32 v61, 7, v21
	v_lshl_add_u32 v63, v3, 2, s1
	v_lshl_add_u32 v64, v4, 2, s1
	v_lshl_add_u32 v65, v5, 2, s1
	v_lshl_add_u32 v66, v6, 2, s1
	v_lshl_add_u32 v67, v7, 2, s1
	v_lshl_add_u32 v73, v16, 2, s1
	v_lshl_add_u32 v77, v21, 2, s1
	v_add_u32_e32 v3, 0x2000, v190
	v_add_u32_e32 v4, 0x2200, v190
	v_add_u32_e32 v5, 0x2400, v190
	v_add_u32_e32 v6, 0x2600, v190
	v_add_u32_e32 v7, 0x2800, v190
	v_add_u32_e32 v16, 0x2a00, v190
	v_add_u32_e32 v21, 0x2c00, v190
	v_add_u32_e32 v30, 0x2e00, v190
	v_add_u32_e32 v31, 0x3000, v190
	v_add_u32_e32 v32, 0x3200, v190
	v_add_u32_e32 v33, 0x3400, v190
	v_add_u32_e32 v34, 0x3600, v190
	v_add_u32_e32 v35, 0x3800, v190
	v_add_u32_e32 v36, 0x3a00, v190
	v_add_u32_e32 v37, 0x3c00, v190
	v_add_u32_e32 v38, 0x3e00, v190
	v_ashrrev_i32_e32 v46, 7, v190
	v_ashrrev_i32_e32 v52, 7, v11
	v_ashrrev_i32_e32 v53, 7, v12
	v_ashrrev_i32_e32 v54, 7, v13
	v_ashrrev_i32_e32 v55, 7, v14
	v_ashrrev_i32_e32 v56, 7, v15
	v_ashrrev_i32_e32 v58, 7, v18
	v_ashrrev_i32_e32 v59, 7, v19
	v_ashrrev_i32_e32 v60, 7, v20
	v_ashrrev_i32_e32 v78, 7, v3
	v_ashrrev_i32_e32 v79, 7, v4
	v_ashrrev_i32_e32 v80, 7, v5
	v_ashrrev_i32_e32 v81, 7, v6
	v_ashrrev_i32_e32 v82, 7, v7
	v_ashrrev_i32_e32 v83, 7, v16
	v_ashrrev_i32_e32 v84, 7, v21
	v_ashrrev_i32_e32 v85, 7, v30
	v_ashrrev_i32_e32 v86, 7, v31
	v_ashrrev_i32_e32 v87, 7, v32
	v_ashrrev_i32_e32 v88, 7, v33
	v_ashrrev_i32_e32 v89, 7, v34
	v_ashrrev_i32_e32 v90, 7, v35
	v_ashrrev_i32_e32 v91, 7, v36
	v_ashrrev_i32_e32 v92, 7, v37
	v_ashrrev_i32_e32 v93, 7, v38
	v_lshl_add_u32 v94, v3, 2, s1
	v_ashrrev_i32_e32 v3, 2, v190
	v_cmp_gt_i32_e64 s[4:5], v2, v46
	v_cmp_gt_i32_e64 s[40:41], v2, v47
	v_cmp_gt_i32_e64 s[42:43], v2, v48
	v_cmp_gt_i32_e64 s[44:45], v2, v49
	v_cmp_gt_i32_e64 s[46:47], v2, v50
	v_cmp_gt_i32_e64 s[48:49], v2, v51
	v_cmp_gt_i32_e64 s[50:51], v2, v52
	v_cmp_gt_i32_e64 s[52:53], v2, v53
	v_cmp_gt_i32_e64 s[54:55], v2, v54
	v_cmp_gt_i32_e64 s[56:57], v2, v55
	v_cmp_gt_i32_e64 s[58:59], v2, v56
	v_cmp_gt_i32_e64 s[60:61], v2, v57
	v_cmp_gt_i32_e64 s[62:63], v2, v58
	v_cmp_gt_i32_e64 s[64:65], v2, v59
	v_cmp_gt_i32_e64 s[66:67], v2, v60
	v_cmp_gt_i32_e64 s[68:69], v2, v61
	v_cmp_gt_i32_e64 s[70:71], v2, v78
	v_cmp_gt_i32_e64 s[72:73], v2, v79
	v_lshl_add_u32 v95, v4, 2, s1
	v_cmp_gt_i32_e64 s[74:75], v2, v80
	v_cmp_gt_i32_e64 s[76:77], v2, v81
	v_cmp_gt_i32_e64 s[78:79], v2, v82
	v_cmp_gt_i32_e64 s[80:81], v2, v83
	v_cmp_gt_i32_e64 s[10:11], v2, v84
	v_cmp_gt_i32_e64 s[84:85], v2, v85
	v_cmp_gt_i32_e64 s[86:87], v2, v86
	v_cmp_gt_i32_e64 s[88:89], v2, v87
	v_cmp_gt_i32_e64 s[90:91], v2, v88
	v_cmp_gt_i32_e64 s[92:93], v2, v89
	v_cmp_gt_i32_e64 s[94:95], v2, v90
	v_cmp_gt_i32_e64 s[96:97], v2, v91
	v_cmp_gt_i32_e64 s[6:7], v2, v92
	v_cmp_gt_i32_e64 s[8:9], v2, v93
	v_and_b32_e32 v2, -4, v3
	v_cmp_lt_i32_e64 s[12:13], -1, v3
	v_or_b32_e32 v4, 3, v3
	v_lshlrev_b32_e32 v3, 5, v190
	s_movk_i32 s0, 0x210
	v_lshl_add_u32 v99, v16, 2, s1
	v_and_b32_e32 v16, 0x1e0, v3
	v_mul_lo_u32 v22, v46, s0
	v_lshl_add_u32 v62, v190, 2, s1
	v_mul_lo_u32 v23, v47, s0
	v_mul_lo_u32 v24, v48, s0
	v_mul_lo_u32 v25, v49, s0
	v_mul_lo_u32 v26, v50, s0
	v_mul_lo_u32 v27, v51, s0
	v_mul_lo_u32 v28, v52, s0
	v_lshl_add_u32 v68, v11, 2, s1
	v_mul_lo_u32 v11, v53, s0
	v_lshl_add_u32 v69, v12, 2, s1
	v_mul_lo_u32 v12, v54, s0
	v_lshl_add_u32 v70, v13, 2, s1
	v_mul_lo_u32 v13, v55, s0
	v_lshl_add_u32 v71, v14, 2, s1
	v_mul_lo_u32 v14, v56, s0
	v_lshl_add_u32 v72, v15, 2, s1
	v_mul_lo_u32 v15, v57, s0
	v_mul_lo_u32 v29, v58, s0
	v_lshl_add_u32 v74, v18, 2, s1
	v_mul_lo_u32 v18, v59, s0
	v_lshl_add_u32 v75, v19, 2, s1
	v_mul_lo_u32 v19, v60, s0
	v_lshl_add_u32 v76, v20, 2, s1
	v_mul_lo_u32 v20, v61, s0
	v_mul_lo_u32 v39, v78, s0
	v_mul_lo_u32 v40, v79, s0
	v_mul_lo_u32 v41, v80, s0
	v_lshl_add_u32 v96, v5, 2, s1
	v_mul_lo_u32 v42, v81, s0
	v_lshl_add_u32 v97, v6, 2, s1
	v_mul_lo_u32 v43, v82, s0
	v_lshl_add_u32 v98, v7, 2, s1
	v_mul_lo_u32 v44, v83, s0
	v_mul_lo_u32 v45, v84, s0
	v_lshl_add_u32 v100, v21, 2, s1
	v_mul_lo_u32 v21, v85, s0
	v_lshl_add_u32 v101, v30, 2, s1
	v_mul_lo_u32 v30, v86, s0
	v_lshl_add_u32 v102, v31, 2, s1
	v_mul_lo_u32 v31, v87, s0
	v_lshl_add_u32 v103, v32, 2, s1
	v_mul_lo_u32 v32, v88, s0
	v_lshl_add_u32 v104, v33, 2, s1
	v_mul_lo_u32 v33, v89, s0
	v_lshl_add_u32 v105, v34, 2, s1
	v_mul_lo_u32 v34, v90, s0
	v_lshl_add_u32 v106, v35, 2, s1
	v_mul_lo_u32 v35, v91, s0
	v_lshl_add_u32 v107, v36, 2, s1
	v_mul_lo_u32 v36, v92, s0
	v_lshl_add_u32 v108, v37, 2, s1
	v_mul_lo_u32 v37, v93, s0
	v_lshl_add_u32 v109, v38, 2, s1
	v_mul_lo_u32 v38, v2, s0
	v_mul_lo_u32 v112, v4, s0
	v_lshl_add_u64 v[6:7], s[20:21], 0, v[16:17]
	s_mov_b64 s[0:1], 0x24600000
	s_waitcnt lgkmcnt(0)
; #define GAS __attribute__((address_space(1)))
; __device__ __forceinline__ void sgu_job(LAS unsigned char* lds, const GAS float* Wh, const GAS float* sbias, const GAS float* VLN, GAS float* U, int m0, int h, int tid) {
;     ...
; #pragma unroll
;     for (int i = 0; i < 4; ++i) { const int t = t0 + i; const float bias = sbias[t]; GAS float* up = U + (size_t)(m0 + t) * 512 + h * 128 + d0;
;         f32x4 u0 = *(const GAS f32x4*)up, u1 = *(const GAS f32x4*)(up + 4);
;         u0.x *= acc[i][0] + bias; u0.y *= acc[i][1] + bias; u0.z *= acc[i][2] + bias; u0.w *= acc[i][3] + bias; u1.x *= acc[i][4] + bias; u1.y *= acc[i][5] + bias; u1.z *= acc[i][6] + bias; u1.w *= acc[i][7] + bias;
;         *(GAS f32x4*)up = u0; *(GAS f32x4*)(up + 4) = u1; }
; __device__ __forceinline__ void m2_phase(ArgP A, int layer, LAS unsigned char* lds, int tid, int lane, int wave, int bid, int G) {
;     ...
;     if (bid >= (G >> 1)) for (int job = bid - (G >> 1); job < 256; job += G - (G >> 1)) { const int b = job >> 6, n = (job >> 2) & 15, h = job & 3;
;         sgu_job(lds, A->in[26] + ((size_t)layer * 4 + h) * 128 * 128, A->in[27] + (layer * 4 + h) * 128, VLN, U, b * SEQ + n * 128, h, tid); }
	v_mov_b32_e32 v8, s16
	v_mov_b32_e32 v9, s17
	v_ashrrev_i32_e32 v191, 31, v190
	v_lshl_add_u64 v[6:7], v[6:7], 0, s[0:1]
	v_readlane_b32 s0, v253, 50
	v_ashrrev_i32_e32 v3, 31, v2
	v_or_b32_e32 v16, 1, v2
	v_or_b32_e32 v110, 2, v2
	v_ashrrev_i32_e32 v5, 31, v4
	v_lshl_add_u64 v[8:9], v[190:191], 2, v[8:9]
	v_add_u32_e32 v111, 1, v4
	v_add_u32_e32 v112, 0, v112
	v_add_u32_e32 v113, 0, v38
	v_lshl_add_u32 v114, v236, 5, s0
	v_add_u32_e32 v115, v10, v22
	v_add_u32_e32 v116, v10, v23
	v_add_u32_e32 v117, v10, v24
	v_add_u32_e32 v118, v10, v25
	v_add_u32_e32 v119, v10, v26
	v_add_u32_e32 v120, v10, v27
	v_add_u32_e32 v121, v10, v28
	v_add_u32_e32 v122, v10, v11
	v_add_u32_e32 v123, v10, v12
	v_add_u32_e32 v124, v10, v13
	v_add_u32_e32 v125, v10, v14
	v_add_u32_e32 v126, v10, v15
	v_add_u32_e32 v127, v10, v29
	v_add_u32_e32 v128, v10, v18
	v_add_u32_e32 v129, v10, v19
	v_add_u32_e32 v130, v10, v20
	v_add_u32_e32 v131, v10, v39
	v_add_u32_e32 v132, v10, v40
	v_add_u32_e32 v133, v10, v41
	v_add_u32_e32 v134, v10, v42
	v_add_u32_e32 v135, v10, v43
	v_add_u32_e32 v136, v10, v44
	v_add_u32_e32 v137, v10, v45
	v_add_u32_e32 v138, v10, v21
	v_add_u32_e32 v139, v10, v30
	v_add_u32_e32 v140, v10, v31
	v_add_u32_e32 v141, v10, v32
	v_add_u32_e32 v142, v10, v33
	v_add_u32_e32 v143, v10, v34
	v_add_u32_e32 v144, v10, v35
	v_add_u32_e32 v145, v10, v36
	v_add_u32_e32 v146, v10, v37
	v_readlane_b32 s16, v251, 4
	s_branch .LBB0_622
.LBB0_621:
	s_mov_b32 s3, s2
	s_lshl_b32 s0, s3, 16
	s_add_u32 s24, s30, s0
	s_addc_u32 s25, s31, 0
	s_add_u32 s98, s24, 0x0
	s_addc_u32 s99, s25, 0
	global_load_dword v12, v10, s[98:99]
	global_load_dword v13, v10, s[98:99] offset:2048
	global_load_dword v14, v11, s[98:99]
	global_load_dword v15, v11, s[98:99] offset:2048
	s_add_u32 s98, s24, 0x4000
	s_addc_u32 s99, s25, 0
	global_load_dword v34, v10, s[98:99]
	global_load_dword v35, v10, s[98:99] offset:2048
	global_load_dword v36, v11, s[98:99]
	global_load_dword v37, v11, s[98:99] offset:2048
	s_add_u32 s98, s24, 0x8000
	s_addc_u32 s99, s25, 0
	global_load_dword v38, v10, s[98:99]
	global_load_dword v39, v10, s[98:99] offset:2048
	global_load_dword v40, v11, s[98:99]
	global_load_dword v41, v11, s[98:99] offset:2048
	s_add_u32 s98, s24, 0xc000
	s_addc_u32 s99, s25, 0
	global_load_dword v42, v10, s[98:99]
	global_load_dword v43, v10, s[98:99] offset:2048
	global_load_dword v44, v11, s[98:99]
	global_load_dword v45, v11, s[98:99] offset:2048
	s_nop 7
	s_waitcnt vmcnt(8)
	v_mul_f32_e32 v18, v18, v12
	v_mul_f32_e32 v19, v19, v13
	v_mul_f32_e32 v20, v20, v14
	v_mul_f32_e32 v21, v21, v15
	v_mul_f32_e32 v22, v22, v34
	v_mul_f32_e32 v23, v23, v35
	v_mul_f32_e32 v24, v24, v36
	v_mul_f32_e32 v25, v25, v37
	s_add_u32 s98, s24, 0x0
	s_addc_u32 s99, s25, 0
	global_store_dword v10, v18, s[98:99]
	global_store_dword v10, v19, s[98:99] offset:2048
	global_store_dword v11, v20, s[98:99]
	global_store_dword v11, v21, s[98:99] offset:2048
	s_add_u32 s98, s24, 0x4000
	s_addc_u32 s99, s25, 0
	global_store_dword v10, v22, s[98:99]
	global_store_dword v10, v23, s[98:99] offset:2048
	global_store_dword v11, v24, s[98:99]
	global_store_dword v11, v25, s[98:99] offset:2048
	s_sub_u32 s3, 3, s2
	s_lshl_b32 s0, s3, 16
	s_add_u32 s24, s30, s0
	s_addc_u32 s25, s31, 0
	s_add_u32 s98, s24, 0x0
	s_addc_u32 s99, s25, 0
	global_load_dword v12, v10, s[98:99]
	global_load_dword v13, v10, s[98:99] offset:2048
	global_load_dword v14, v11, s[98:99]
	global_load_dword v15, v11, s[98:99] offset:2048
	s_add_u32 s98, s24, 0x4000
	s_addc_u32 s99, s25, 0
	global_load_dword v34, v10, s[98:99]
	global_load_dword v35, v10, s[98:99] offset:2048
	global_load_dword v36, v11, s[98:99]
	global_load_dword v37, v11, s[98:99] offset:2048
	s_waitcnt vmcnt(16)
	s_mov_b32 s3, s2
	s_lshl_b32 s0, s3, 16
	s_add_u32 s24, s30, s0
	s_addc_u32 s25, s31, 0
	v_mul_f32_e32 v26, v26, v38
	v_mul_f32_e32 v27, v27, v39
	v_mul_f32_e32 v28, v28, v40
	v_mul_f32_e32 v29, v29, v41
	v_mul_f32_e32 v30, v30, v42
	v_mul_f32_e32 v31, v31, v43
	v_mul_f32_e32 v32, v32, v44
	v_mul_f32_e32 v33, v33, v45
	s_add_u32 s98, s24, 0x8000
	s_addc_u32 s99, s25, 0
	global_store_dword v10, v26, s[98:99]
	global_store_dword v10, v27, s[98:99] offset:2048
	global_store_dword v11, v28, s[98:99]
	global_store_dword v11, v29, s[98:99] offset:2048
	s_add_u32 s98, s24, 0xc000
	s_addc_u32 s99, s25, 0
	global_store_dword v10, v30, s[98:99]
	global_store_dword v10, v31, s[98:99] offset:2048
	global_store_dword v11, v32, s[98:99]
	global_store_dword v11, v33, s[98:99] offset:2048
	s_sub_u32 s3, 3, s2
	s_lshl_b32 s0, s3, 16
	s_add_u32 s24, s30, s0
	s_addc_u32 s25, s31, 0
	s_add_u32 s98, s24, 0x8000
	s_addc_u32 s99, s25, 0
	global_load_dword v38, v10, s[98:99]
	global_load_dword v39, v10, s[98:99] offset:2048
	global_load_dword v40, v11, s[98:99]
	global_load_dword v41, v11, s[98:99] offset:2048
	s_add_u32 s98, s24, 0xc000
	s_addc_u32 s99, s25, 0
	global_load_dword v42, v10, s[98:99]
	global_load_dword v43, v10, s[98:99] offset:2048
	global_load_dword v44, v11, s[98:99]
	global_load_dword v45, v11, s[98:99] offset:2048
	s_waitcnt vmcnt(16)
	v_mul_f32_e32 v148, v148, v12
	v_mul_f32_e32 v149, v149, v13
	v_mul_f32_e32 v150, v150, v14
	v_mul_f32_e32 v151, v151, v15
	v_mul_f32_e32 v152, v152, v34
	v_mul_f32_e32 v153, v153, v35
	v_mul_f32_e32 v154, v154, v36
	v_mul_f32_e32 v155, v155, v37
	s_add_u32 s98, s24, 0x0
	s_addc_u32 s99, s25, 0
	global_store_dword v10, v148, s[98:99]
	global_store_dword v10, v149, s[98:99] offset:2048
	global_store_dword v11, v150, s[98:99]
	global_store_dword v11, v151, s[98:99] offset:2048
	s_add_u32 s98, s24, 0x4000
	s_addc_u32 s99, s25, 0
	global_store_dword v10, v152, s[98:99]
	global_store_dword v10, v153, s[98:99] offset:2048
	global_store_dword v11, v154, s[98:99]
	global_store_dword v11, v155, s[98:99] offset:2048
	s_waitcnt vmcnt(8)
	v_mul_f32_e32 v156, v156, v38
	v_mul_f32_e32 v157, v157, v39
	v_mul_f32_e32 v158, v158, v40
	v_mul_f32_e32 v159, v159, v41
	v_mul_f32_e32 v160, v160, v42
	v_mul_f32_e32 v161, v161, v43
	v_mul_f32_e32 v162, v162, v44
	v_mul_f32_e32 v163, v163, v45
	s_add_u32 s98, s24, 0x8000
	s_addc_u32 s99, s25, 0
	global_store_dword v10, v156, s[98:99]
	global_store_dword v10, v157, s[98:99] offset:2048
	global_store_dword v11, v158, s[98:99]
	global_store_dword v11, v159, s[98:99] offset:2048
	s_add_u32 s98, s24, 0xc000
	s_addc_u32 s99, s25, 0
	global_store_dword v10, v160, s[98:99]
	global_store_dword v10, v161, s[98:99] offset:2048
	global_store_dword v11, v162, s[98:99]
	global_store_dword v11, v163, s[98:99] offset:2048
	s_addk_i32 s16, 0x100
	s_cmpk_lt_i32 s16, 0x100
	s_barrier
	s_cbranch_scc0 .LBB0_626

; #define LAS __attribute__((address_space(3)))
; #define GAS __attribute__((address_space(1)))
; #define R4_ISSUE(cc, slot) do { const GAS float* g_ = gp + (size_t)(cc) * 2048; LAS float* l_ = ring + (slot) * 1536; _Pragma("unroll") for (int i_ = 0; i_ < 6; ++i_) \
;         __builtin_amdgcn_global_load_lds((const GAS unsigned*)(g_ + off[i_]), (LAS unsigned*)(l_ + i_ * 256), 16, 0, 0); } while (0)
; #define R4_LOAD(o, sb_) do { const LAS float* sb = (sb_); (o).r = *(const LAS f32x4*)(sb + cgp * 4); (o).w = *(const LAS f32x4*)(sb + 64 + cgp * 4); (o).k = *(const LAS f32x4*)(sb + 128 + cgp * 4); \
;         (o).a = *(const LAS f32x4*)(sb + 256 + cgp * 4); (o).b = *(const LAS f32x4*)(sb + 320 + cgp * 4); (o).vv = sb[192 + rq * 4 + rl]; asm volatile("" ::: "memory"); } while (0)
; __device__ __forceinline__ void rwkv_prompt_wave4(LAS float* ring, const GAS float* RW, int mbase, int h, int rq, GAS float* Sout, GAS float* YR, int lane) {
;     ...
;     const GAS float* gp = RW + (size_t)mbase * 512 + h * 64;
;     constexpr int NCH = SEQ / 4;
;     ...
;     struct R4Ops { f32x4 r, w, k, a, b; float vv; };
;     ...
;     for (int cc = 0; cc < 3; ++cc) R4_ISSUE(cc, cc);
;     float ykeep = 0.f;
;     R4Ops oA, oB, oC, oD;
;     asm volatile("s_waitcnt vmcnt(12)" ::: "memory");
;     R4_LOAD(oA, ring); R4_LOAD(oB, ring + 384);
;     for (int ci = 0; ci < NCH; ++ci) {
;         { const int cn = ci + 3; const int cl = cn < NCH ? cn : NCH - 1; R4_ISSUE(cl, cn % R4_NS); }
;         const LAS float* cb = ring + (ci % R4_NS) * 1536; const LAS float* nb = ring + ((ci + 1) % R4_NS) * 1536;
;         R4_LOAD(oC, cb + 768);  R4_STEP(oA, 0);
;         R4_LOAD(oD, cb + 1152); R4_STEP(oB, 1);
;         asm volatile("s_waitcnt vmcnt(12)" ::: "memory");
;         R4_LOAD(oA, nb);        R4_STEP(oC, 2);
;         R4_LOAD(oB, nb + 384);  R4_STEP(oD, 3);
;         if (cgp < 4) YR[(size_t)(mbase + ci * 4 + cgp) * 512 + h * 64 + rq * 4 + rl] = ykeep;
.LBB0_701:
	v_readlane_b32 s68, v251, 2
	s_andn2_b64 vcc, exec, s[0:1]
	v_readlane_b32 s69, v251, 3
	s_movk_i32 s36, 0x2000
	s_movk_i32 s37, 0x4000
	s_cbranch_vccnz .LBB0_709
	v_readlane_b32 s0, v252, 16
	s_add_i32 s3, s24, s0
	s_cmpk_gt_i32 s3, 0x1ff
	s_cselect_b64 s[0:1], -1, 0
	s_or_b64 s[0:1], s[10:11], s[0:1]
	s_and_b64 vcc, exec, s[0:1]
	s_cbranch_vccnz .Lld_entry
	s_mov_b32 s14, 0
	s_waitcnt vmcnt(5)
	v_or_b32_e32 v2, 0x100, v192
	s_movk_i32 s0, 0x17f
	v_cmp_lt_u32_e32 vcc, s0, v2
	s_waitcnt vmcnt(4)
	v_mov_b32_e32 v3, 0xfffffe80
	v_and_b32_e32 v1, 60, v192
	v_cndmask_b32_e32 v3, 0, v3, vcc
	v_add_u32_e32 v2, v3, v2
	v_lshrrev_b32_e32 v2, 6, v2
	v_mov_b32_e32 v3, 0x200
	v_mul_i32_i24_e32 v2, 0x440000, v2
	v_cndmask_b32_e32 v3, 0, v3, vcc
	v_or3_b32 v46, v2, v3, v1
	v_or_b32_e32 v3, 0x400, v192
	s_waitcnt vmcnt(2)
	v_mul_u32_u24_e32 v5, 0x2ab, v3
	v_lshrrev_b32_e32 v5, 18, v5
	s_movk_i32 s0, 0xfe80
	v_mad_i32_i24 v3, v5, s0, v3
	v_lshrrev_b32_e32 v3, 6, v3
	s_mov_b32 s0, 0x440000
	v_mul_lo_u32 v3, v3, s0
	s_load_dwordx2 s[0:1], s[28:29], 0x130
	v_add_u32_e32 v2, 0x80, v192
	v_lshrrev_b32_e32 v65, 4, v191
	v_lshrrev_b32_e32 v2, 6, v2
	v_mul_u32_u24_e32 v0, 0x440000, v65
	v_mul_u32_u24_e32 v2, 0x440000, v2
	v_lshlrev_b32_e32 v52, 2, v65
	v_mov_b32_e32 v53, v17
	v_or_b32_e32 v0, v0, v1
	v_or_b32_e32 v2, v2, v1
	v_lshlrev_b32_e32 v5, 9, v5
	v_lshl_add_u64 v[54:55], s[12:13], 0, v[52:53]
	s_waitcnt lgkmcnt(0)
	s_add_u32 s12, s0, 0x4400000
	v_or_b32_e32 v4, 0x200, v2
	s_waitcnt vmcnt(1)
	v_or_b32_e32 v6, 0x400, v0
	v_or3_b32 v48, v3, v5, v1
	v_mov_b32_e32 v5, v17
	v_lshlrev_b32_e32 v8, 2, v236
	v_lshlrev_b32_e32 v67, 4, v236
	s_addc_u32 s13, s1, 0
	s_lshl_b32 s0, s24, 2
	v_readlane_b32 s1, v253, 36
	v_or_b32_e32 v50, 0x600, v2
	v_mov_b32_e32 v47, v17
	v_mov_b32_e32 v49, v17
	v_mov_b32_e32 v51, v17
	v_add_u32_e32 v68, s14, v67
	v_cmp_eq_u32_e32 vcc, 0, v236
	v_cmp_eq_u32_e64 s[4:5], 1, v236
	v_cmp_eq_u32_e64 s[6:7], 2, v236
	v_cmp_eq_u32_e64 s[8:9], 3, v236
	v_cmp_gt_u32_e64 s[40:41], 4, v236
	s_add_i32 s15, s1, s0
	v_lshlrev_b32_e32 v53, 2, v0
	v_lshlrev_b32_e32 v16, 2, v2
	v_lshlrev_b32_e32 v69, 2, v6
	v_lshlrev_b64 v[56:57], 2, v[4:5]
	v_lshlrev_b32_e32 v58, 2, v8
	s_lshl_b32 s22, s24, 13
	s_add_i32 s22, s22, 0x18000
	v_lshl_add_u32 v50, v191, 2, s22
	s_waitcnt vmcnt(0)
	s_branch .LBB0_705
.LBB0_704:
	s_ashr_i32 s1, s17, 31
	s_add_u32 s0, s17, s2
	s_addc_u32 s1, s1, 0
	s_lshl_b64 s[0:1], s[0:1], 17
	s_add_u32 s0, s12, s0
	s_addc_u32 s1, s13, s1
	s_lshl_b32 s10, s16, 14
	s_add_u32 s0, s0, s10
	s_addc_u32 s1, s1, 0
	s_waitcnt lgkmcnt(0)
	s_barrier
	v_lshlrev_b32_e32 v0, 8, v59
	v_mov_b32_e32 v1, v17
	v_lshl_add_u64 v[0:1], s[0:1], 0, v[0:1]
	v_readlane_b32 s0, v252, 17
	s_waitcnt vmcnt(0)
	s_add_i32 s3, s3, s0
	v_readlane_b32 s0, v253, 29
	v_mov_b32_e32 v59, v17
	s_add_i32 s15, s15, s0
	v_lshl_add_u64 v[0:1], v[0:1], 0, v[58:59]
	s_cmpk_gt_i32 s3, 0x1ff
	global_store_dwordx4 v[0:1], v[42:45], off
	s_cbranch_scc1 .LBB0_709
.LBB0_705:
	s_lshl_b32 s0, s15, 2
	s_ashr_i32 s17, s3, 7
	s_and_b32 s24, s0, 0xf0
	s_lshl_b32 s0, s17, 11
	s_bfe_u32 s16, s3, 0x30004
	s_lshl_b32 s82, s16, 8
	s_mov_b32 s21, s83
	v_mov_b32_e32 v71, 0
	v_or_b32_e32 v62, s0, v236
	v_or_b32_e32 v70, s24, v52
	v_mov_b32_e32 v44, 0
	v_mov_b32_e32 v45, v71
	s_lshl_b32 s1, s3, 2
	s_and_b32 s1, s1, 60
	v_or_b32_e32 v59, s1, v65
	v_lshl_add_u32 v42, v59, 2, s14
	s_barrier
	ds_read_b128 v[26:29], v68 offset:1024
	ds_read_b128 v[4:7], v68 offset:256
	ds_read_b128 v[8:11], v68 offset:512
	ds_read_b32 v64, v42 offset:768
	ds_read_b128 v[22:25], v68 offset:1280
	ds_read_b128 v[0:3], v68
	ds_read_b128 v[38:41], v68 offset:2560
	ds_read_b128 v[18:21], v68 offset:1792
	ds_read_b128 v[30:33], v68 offset:2048
	ds_read_b32 v66, v42 offset:2304
	ds_read_b128 v[34:37], v68 offset:2816
	ds_read_b128 v[12:15], v68 offset:1536
	s_mov_b32 s21, 0
	s_mov_b32 s22, 0
	s_mov_b32 s23, 3
	s_movk_i32 s27, 0x1800
	v_mov_b32_e32 v46, v67
	v_mov_b32_e32 v47, v70
	v_mov_b32_e32 v42, 0
	v_mov_b32_e32 v43, v71
	s_waitcnt lgkmcnt(0)
	s_branch .LBB0_707
.LBB0_707:
	s_add_i32 s23, s23, -1
	s_cmp_lg_u32 s23, 0
	s_cbranch_scc1 .Lrw_nobar
	s_mov_b32 s23, 2
	s_waitcnt lgkmcnt(0)
	s_barrier
.Lrw_nobar:
	s_waitcnt lgkmcnt(8)
	v_pk_mul_f32 v[28:29], v[44:45], v[28:29]
	v_pk_mul_f32 v[8:9], v[64:65], v[8:9] op_sel_hi:[0,1]
	v_pk_fma_f32 v[26:27], v[42:43], v[26:27], v[28:29]
	v_pk_mul_f32 v[10:11], v[64:65], v[10:11] op_sel_hi:[0,1]
	v_add_f32_e32 v26, v26, v27
	ds_read_b128 v[84:87], v46 offset:4096
	v_pk_fma_f32 v[4:5], v[42:43], v[4:5], v[8:9]
	v_add_f32_dpp v26, v26, v26 quad_perm:[1,0,3,2] row_mask:0xf bank_mask:0xf bound_ctrl:1
	ds_read_b128 v[76:79], v46 offset:3328
	v_pk_fma_f32 v[6:7], v[44:45], v[6:7], v[10:11]
	v_add_f32_dpp v26, v26, v26 quad_perm:[2,3,0,1] row_mask:0xf bank_mask:0xf bound_ctrl:1
	ds_read_b128 v[80:83], v46 offset:3584
	ds_read_b32 v108, v47 offset:3840
	v_add_f32_dpp v26, v26, v26 row_half_mirror row_mask:0xf bank_mask:0xf bound_ctrl:1
	ds_read_b128 v[88:91], v46 offset:4352
	ds_read_b128 v[72:75], v46 offset:3072
	v_add_f32_dpp v26, v26, v26 row_mirror row_mask:0xf bank_mask:0xf bound_ctrl:1
	v_pk_fma_f32 v[4:5], v[22:23], v[26:27], v[4:5] op_sel_hi:[1,0,1]
	v_pk_fma_f32 v[6:7], v[24:25], v[26:27], v[6:7] op_sel_hi:[1,0,1]
	v_add_u32_e32 v51, s22, v50
	v_add_u32_e32 v48, s27, v67
	v_add_u32_e32 v49, s27, v70
	s_add_i32 s27, s27, 0x1800
	s_cmp_eq_u32 s27, 0x18000
	s_cselect_b32 s27, 0, s27
	s_add_i32 s22, s22, 0x400
	s_and_b32 s22, s22, 0x1fff
	s_waitcnt lgkmcnt(7)
; #define LAS __attribute__((address_space(3)))
; #define R4_ISSUE(cc, slot) do { const GAS float* g_ = gp + (size_t)(cc) * 2048; LAS float* l_ = ring + (slot) * 1536; _Pragma("unroll") for (int i_ = 0; i_ < 6; ++i_) \
;         __builtin_amdgcn_global_load_lds((const GAS unsigned*)(g_ + off[i_]), (LAS unsigned*)(l_ + i_ * 256), 16, 0, 0); } while (0)
; #define R4_LOAD(o, sb_) do { const LAS float* sb = (sb_); (o).r = *(const LAS f32x4*)(sb + cgp * 4); (o).w = *(const LAS f32x4*)(sb + 64 + cgp * 4); (o).k = *(const LAS f32x4*)(sb + 128 + cgp * 4); \
;         (o).a = *(const LAS f32x4*)(sb + 256 + cgp * 4); (o).b = *(const LAS f32x4*)(sb + 320 + cgp * 4); (o).vv = sb[192 + rq * 4 + rl]; asm volatile("" ::: "memory"); } while (0)
; __device__ __forceinline__ void rwkv_prompt_wave4(LAS float* ring, const GAS float* RW, int mbase, int h, int rq, GAS float* Sout, GAS float* YR, int lane) {
;     ...
;     for (int cc = 0; cc < 3; ++cc) R4_ISSUE(cc, cc);
;     float ykeep = 0.f;
;     R4Ops oA, oB, oC, oD;
;     asm volatile("s_waitcnt vmcnt(12)" ::: "memory");
;     R4_LOAD(oA, ring); R4_LOAD(oB, ring + 384);
;     for (int ci = 0; ci < NCH; ++ci) {
;         { const int cn = ci + 3; const int cl = cn < NCH ? cn : NCH - 1; R4_ISSUE(cl, cn % R4_NS); }
;         const LAS float* cb = ring + (ci % R4_NS) * 1536; const LAS float* nb = ring + ((ci + 1) % R4_NS) * 1536;
;         R4_LOAD(oC, cb + 768);  R4_STEP(oA, 0);
;         R4_LOAD(oD, cb + 1152); R4_STEP(oB, 1);
;         asm volatile("s_waitcnt vmcnt(12)" ::: "memory");
;         R4_LOAD(oA, nb);        R4_STEP(oC, 2);
;         R4_LOAD(oB, nb + 384);  R4_STEP(oD, 3);
;         if (cgp < 4) YR[(size_t)(mbase + ci * 4 + cgp) * 512 + h * 64 + rq * 4 + rl] = ykeep;
	v_pk_mul_f32 v[40:41], v[6:7], v[40:41]
	v_pk_mul_f32 v[30:31], v[66:67], v[30:31] op_sel_hi:[0,1]
	v_pk_fma_f32 v[38:39], v[4:5], v[38:39], v[40:41]
	v_pk_mul_f32 v[32:33], v[66:67], v[32:33] op_sel_hi:[0,1]
	v_add_f32_e32 v38, v38, v39
	v_pk_mul_f32 v[2:3], v[2:3], v[6:7]
	v_pk_fma_f32 v[18:19], v[4:5], v[18:19], v[30:31]
	v_add_f32_dpp v38, v38, v38 quad_perm:[1,0,3,2] row_mask:0xf bank_mask:0xf bound_ctrl:1
	ds_read_b128 v[100:103], v46 offset:5632
	v_pk_fma_f32 v[20:21], v[6:7], v[20:21], v[32:33]
	v_add_f32_dpp v38, v38, v38 quad_perm:[2,3,0,1] row_mask:0xf bank_mask:0xf bound_ctrl:1
	v_pk_fma_f32 v[0:1], v[0:1], v[4:5], v[2:3]
	ds_read_b128 v[42:45], v46 offset:4864
	v_add_f32_dpp v38, v38, v38 row_half_mirror row_mask:0xf bank_mask:0xf bound_ctrl:1
	v_add_f32_e32 v0, v0, v1
	ds_write_b32 v51, v0 offset:0
	v_add_f32_dpp v38, v38, v38 row_mirror row_mask:0xf bank_mask:0xf bound_ctrl:1
	v_pk_fma_f32 v[18:19], v[34:35], v[38:39], v[18:19] op_sel_hi:[1,0,1]
	v_pk_fma_f32 v[20:21], v[36:37], v[38:39], v[20:21] op_sel_hi:[1,0,1]
	ds_read_b128 v[96:99], v46 offset:5120
	ds_read_b32 v110, v47 offset:5376
	ds_read_b128 v[104:107], v46 offset:5888
	ds_read_b128 v[92:95], v46 offset:4608
	s_waitcnt lgkmcnt(7)
	v_pk_mul_f32 v[86:87], v[20:21], v[86:87]
	v_pk_mul_f32 v[80:81], v[108:109], v[80:81] op_sel_hi:[0,1]
	v_pk_fma_f32 v[84:85], v[18:19], v[84:85], v[86:87]
	v_pk_mul_f32 v[82:83], v[108:109], v[82:83] op_sel_hi:[0,1]
	v_add_f32_e32 v84, v84, v85
	v_pk_mul_f32 v[14:15], v[14:15], v[20:21]
	v_pk_fma_f32 v[76:77], v[18:19], v[76:77], v[80:81]
	v_add_f32_dpp v84, v84, v84 quad_perm:[1,0,3,2] row_mask:0xf bank_mask:0xf bound_ctrl:1
	ds_read_b128 v[26:29], v48 offset:1024
	v_pk_fma_f32 v[78:79], v[20:21], v[78:79], v[82:83]
	v_add_f32_dpp v84, v84, v84 quad_perm:[2,3,0,1] row_mask:0xf bank_mask:0xf bound_ctrl:1
	v_pk_fma_f32 v[12:13], v[12:13], v[18:19], v[14:15]
	ds_read_b128 v[4:7], v48 offset:256
	v_add_f32_dpp v84, v84, v84 row_half_mirror row_mask:0xf bank_mask:0xf bound_ctrl:1
	v_add_f32_e32 v12, v12, v13
	ds_write_b32 v51, v12 offset:256
	v_add_f32_dpp v84, v84, v84 row_mirror row_mask:0xf bank_mask:0xf bound_ctrl:1
	v_pk_fma_f32 v[76:77], v[88:89], v[84:85], v[76:77] op_sel_hi:[1,0,1]
	v_pk_fma_f32 v[78:79], v[90:91], v[84:85], v[78:79] op_sel_hi:[1,0,1]
	ds_read_b128 v[8:11], v48 offset:512
	ds_read_b32 v64, v49 offset:768
	ds_read_b128 v[22:25], v48 offset:1280
	ds_read_b128 v[0:3], v48 offset:0
	s_waitcnt lgkmcnt(7)
	v_pk_mul_f32 v[102:103], v[78:79], v[102:103]
	v_pk_mul_f32 v[96:97], v[110:111], v[96:97] op_sel_hi:[0,1]
	v_pk_fma_f32 v[100:101], v[76:77], v[100:101], v[102:103]
	v_pk_mul_f32 v[98:99], v[110:111], v[98:99] op_sel_hi:[0,1]
	v_add_f32_e32 v100, v100, v101
	v_pk_mul_f32 v[74:75], v[74:75], v[78:79]
	v_pk_fma_f32 v[42:43], v[76:77], v[42:43], v[96:97]
	v_add_f32_dpp v100, v100, v100 quad_perm:[1,0,3,2] row_mask:0xf bank_mask:0xf bound_ctrl:1
	ds_read_b128 v[38:41], v48 offset:2560
	v_pk_fma_f32 v[44:45], v[78:79], v[44:45], v[98:99]
	v_add_f32_dpp v100, v100, v100 quad_perm:[2,3,0,1] row_mask:0xf bank_mask:0xf bound_ctrl:1
	v_pk_fma_f32 v[72:73], v[72:73], v[76:77], v[74:75]
	ds_read_b128 v[18:21], v48 offset:1792
	v_add_f32_dpp v100, v100, v100 row_half_mirror row_mask:0xf bank_mask:0xf bound_ctrl:1
	v_add_f32_e32 v72, v72, v73
	ds_write_b32 v51, v72 offset:512
	v_add_f32_dpp v100, v100, v100 row_mirror row_mask:0xf bank_mask:0xf bound_ctrl:1
	v_pk_fma_f32 v[42:43], v[104:105], v[100:101], v[42:43] op_sel_hi:[1,0,1]
	v_pk_fma_f32 v[44:45], v[106:107], v[100:101], v[44:45] op_sel_hi:[1,0,1]
	ds_read_b128 v[30:33], v48 offset:2048
	ds_read_b32 v66, v49 offset:2304
	ds_read_b128 v[34:37], v48 offset:2816
	ds_read_b128 v[12:15], v48 offset:1536
	v_pk_mul_f32 v[94:95], v[94:95], v[44:45]
	s_add_i32 s21, s21, 1
	v_pk_fma_f32 v[92:93], v[92:93], v[42:43], v[94:95]
	s_nop 0
	v_add_f32_e32 v92, v92, v93
	ds_write_b32 v51, v92 offset:768
	s_waitcnt lgkmcnt(8)
	v_pk_mul_f32 v[28:29], v[44:45], v[28:29]
	v_pk_mul_f32 v[8:9], v[64:65], v[8:9] op_sel_hi:[0,1]
	v_pk_fma_f32 v[26:27], v[42:43], v[26:27], v[28:29]
	v_pk_mul_f32 v[10:11], v[64:65], v[10:11] op_sel_hi:[0,1]
	v_add_f32_e32 v26, v26, v27
	ds_read_b128 v[84:87], v48 offset:4096
	v_pk_fma_f32 v[4:5], v[42:43], v[4:5], v[8:9]
	v_add_f32_dpp v26, v26, v26 quad_perm:[1,0,3,2] row_mask:0xf bank_mask:0xf bound_ctrl:1
	ds_read_b128 v[76:79], v48 offset:3328
	v_pk_fma_f32 v[6:7], v[44:45], v[6:7], v[10:11]
	v_add_f32_dpp v26, v26, v26 quad_perm:[2,3,0,1] row_mask:0xf bank_mask:0xf bound_ctrl:1
	ds_read_b128 v[80:83], v48 offset:3584
	ds_read_b32 v108, v49 offset:3840
	v_add_f32_dpp v26, v26, v26 row_half_mirror row_mask:0xf bank_mask:0xf bound_ctrl:1
	ds_read_b128 v[88:91], v48 offset:4352
	ds_read_b128 v[72:75], v48 offset:3072
	v_add_f32_dpp v26, v26, v26 row_mirror row_mask:0xf bank_mask:0xf bound_ctrl:1
	v_pk_fma_f32 v[4:5], v[22:23], v[26:27], v[4:5] op_sel_hi:[1,0,1]
	v_pk_fma_f32 v[6:7], v[24:25], v[26:27], v[6:7] op_sel_hi:[1,0,1]
	v_add_u32_e32 v51, s22, v50
	v_add_u32_e32 v46, s27, v67
	v_add_u32_e32 v47, s27, v70
	s_add_i32 s27, s27, 0x1800
	s_cmp_eq_u32 s27, 0x18000
	s_cselect_b32 s27, 0, s27
	s_add_i32 s22, s22, 0x400
	s_and_b32 s22, s22, 0x1fff
	s_waitcnt lgkmcnt(7)
; #define LAS __attribute__((address_space(3)))
; #define R4_ISSUE(cc, slot) do { const GAS float* g_ = gp + (size_t)(cc) * 2048; LAS float* l_ = ring + (slot) * 1536; _Pragma("unroll") for (int i_ = 0; i_ < 6; ++i_) \
;         __builtin_amdgcn_global_load_lds((const GAS unsigned*)(g_ + off[i_]), (LAS unsigned*)(l_ + i_ * 256), 16, 0, 0); } while (0)
; #define R4_LOAD(o, sb_) do { const LAS float* sb = (sb_); (o).r = *(const LAS f32x4*)(sb + cgp * 4); (o).w = *(const LAS f32x4*)(sb + 64 + cgp * 4); (o).k = *(const LAS f32x4*)(sb + 128 + cgp * 4); \
;         (o).a = *(const LAS f32x4*)(sb + 256 + cgp * 4); (o).b = *(const LAS f32x4*)(sb + 320 + cgp * 4); (o).vv = sb[192 + rq * 4 + rl]; asm volatile("" ::: "memory"); } while (0)
; __device__ __forceinline__ void rwkv_prompt_wave4(LAS float* ring, const GAS float* RW, int mbase, int h, int rq, GAS float* Sout, GAS float* YR, int lane) {
;     ...
;     for (int cc = 0; cc < 3; ++cc) R4_ISSUE(cc, cc);
;     float ykeep = 0.f;
;     R4Ops oA, oB, oC, oD;
;     asm volatile("s_waitcnt vmcnt(12)" ::: "memory");
;     R4_LOAD(oA, ring); R4_LOAD(oB, ring + 384);
;     for (int ci = 0; ci < NCH; ++ci) {
;         { const int cn = ci + 3; const int cl = cn < NCH ? cn : NCH - 1; R4_ISSUE(cl, cn % R4_NS); }
;         const LAS float* cb = ring + (ci % R4_NS) * 1536; const LAS float* nb = ring + ((ci + 1) % R4_NS) * 1536;
;         R4_LOAD(oC, cb + 768);  R4_STEP(oA, 0);
;         R4_LOAD(oD, cb + 1152); R4_STEP(oB, 1);
;         asm volatile("s_waitcnt vmcnt(12)" ::: "memory");
;         R4_LOAD(oA, nb);        R4_STEP(oC, 2);
;         R4_LOAD(oB, nb + 384);  R4_STEP(oD, 3);
;         if (cgp < 4) YR[(size_t)(mbase + ci * 4 + cgp) * 512 + h * 64 + rq * 4 + rl] = ykeep;
;     }
	v_pk_mul_f32 v[40:41], v[6:7], v[40:41]
	v_pk_mul_f32 v[30:31], v[66:67], v[30:31] op_sel_hi:[0,1]
	v_pk_fma_f32 v[38:39], v[4:5], v[38:39], v[40:41]
	v_pk_mul_f32 v[32:33], v[66:67], v[32:33] op_sel_hi:[0,1]
	v_add_f32_e32 v38, v38, v39
	v_pk_mul_f32 v[2:3], v[2:3], v[6:7]
	v_pk_fma_f32 v[18:19], v[4:5], v[18:19], v[30:31]
	v_add_f32_dpp v38, v38, v38 quad_perm:[1,0,3,2] row_mask:0xf bank_mask:0xf bound_ctrl:1
	ds_read_b128 v[100:103], v48 offset:5632
	v_pk_fma_f32 v[20:21], v[6:7], v[20:21], v[32:33]
	v_add_f32_dpp v38, v38, v38 quad_perm:[2,3,0,1] row_mask:0xf bank_mask:0xf bound_ctrl:1
	v_pk_fma_f32 v[0:1], v[0:1], v[4:5], v[2:3]
	ds_read_b128 v[42:45], v48 offset:4864
	v_add_f32_dpp v38, v38, v38 row_half_mirror row_mask:0xf bank_mask:0xf bound_ctrl:1
	v_add_f32_e32 v0, v0, v1
	ds_write_b32 v51, v0 offset:0
	v_add_f32_dpp v38, v38, v38 row_mirror row_mask:0xf bank_mask:0xf bound_ctrl:1
	v_pk_fma_f32 v[18:19], v[34:35], v[38:39], v[18:19] op_sel_hi:[1,0,1]
	v_pk_fma_f32 v[20:21], v[36:37], v[38:39], v[20:21] op_sel_hi:[1,0,1]
	ds_read_b128 v[96:99], v48 offset:5120
	ds_read_b32 v110, v49 offset:5376
	ds_read_b128 v[104:107], v48 offset:5888
	ds_read_b128 v[92:95], v48 offset:4608
	s_waitcnt lgkmcnt(7)
	v_pk_mul_f32 v[86:87], v[20:21], v[86:87]
	v_pk_mul_f32 v[80:81], v[108:109], v[80:81] op_sel_hi:[0,1]
	v_pk_fma_f32 v[84:85], v[18:19], v[84:85], v[86:87]
	v_pk_mul_f32 v[82:83], v[108:109], v[82:83] op_sel_hi:[0,1]
	v_add_f32_e32 v84, v84, v85
	v_pk_mul_f32 v[14:15], v[14:15], v[20:21]
	v_pk_fma_f32 v[76:77], v[18:19], v[76:77], v[80:81]
	v_add_f32_dpp v84, v84, v84 quad_perm:[1,0,3,2] row_mask:0xf bank_mask:0xf bound_ctrl:1
	ds_read_b128 v[26:29], v46 offset:1024
	v_pk_fma_f32 v[78:79], v[20:21], v[78:79], v[82:83]
	v_add_f32_dpp v84, v84, v84 quad_perm:[2,3,0,1] row_mask:0xf bank_mask:0xf bound_ctrl:1
	v_pk_fma_f32 v[12:13], v[12:13], v[18:19], v[14:15]
	ds_read_b128 v[4:7], v46 offset:256
	v_add_f32_dpp v84, v84, v84 row_half_mirror row_mask:0xf bank_mask:0xf bound_ctrl:1
	v_add_f32_e32 v12, v12, v13
	ds_write_b32 v51, v12 offset:256
	v_add_f32_dpp v84, v84, v84 row_mirror row_mask:0xf bank_mask:0xf bound_ctrl:1
	v_pk_fma_f32 v[76:77], v[88:89], v[84:85], v[76:77] op_sel_hi:[1,0,1]
	v_pk_fma_f32 v[78:79], v[90:91], v[84:85], v[78:79] op_sel_hi:[1,0,1]
	ds_read_b128 v[8:11], v46 offset:512
	ds_read_b32 v64, v47 offset:768
	ds_read_b128 v[22:25], v46 offset:1280
	ds_read_b128 v[0:3], v46 offset:0
	s_waitcnt lgkmcnt(7)
	v_pk_mul_f32 v[102:103], v[78:79], v[102:103]
	v_pk_mul_f32 v[96:97], v[110:111], v[96:97] op_sel_hi:[0,1]
	v_pk_fma_f32 v[100:101], v[76:77], v[100:101], v[102:103]
	v_pk_mul_f32 v[98:99], v[110:111], v[98:99] op_sel_hi:[0,1]
	v_add_f32_e32 v100, v100, v101
	v_pk_mul_f32 v[74:75], v[74:75], v[78:79]
	v_pk_fma_f32 v[42:43], v[76:77], v[42:43], v[96:97]
	v_add_f32_dpp v100, v100, v100 quad_perm:[1,0,3,2] row_mask:0xf bank_mask:0xf bound_ctrl:1
	ds_read_b128 v[38:41], v46 offset:2560
	v_pk_fma_f32 v[44:45], v[78:79], v[44:45], v[98:99]
	v_add_f32_dpp v100, v100, v100 quad_perm:[2,3,0,1] row_mask:0xf bank_mask:0xf bound_ctrl:1
	v_pk_fma_f32 v[72:73], v[72:73], v[76:77], v[74:75]
	ds_read_b128 v[18:21], v46 offset:1792
	v_add_f32_dpp v100, v100, v100 row_half_mirror row_mask:0xf bank_mask:0xf bound_ctrl:1
	v_add_f32_e32 v72, v72, v73
	ds_write_b32 v51, v72 offset:512
	v_add_f32_dpp v100, v100, v100 row_mirror row_mask:0xf bank_mask:0xf bound_ctrl:1
	v_pk_fma_f32 v[42:43], v[104:105], v[100:101], v[42:43] op_sel_hi:[1,0,1]
	v_pk_fma_f32 v[44:45], v[106:107], v[100:101], v[44:45] op_sel_hi:[1,0,1]
	ds_read_b128 v[30:33], v46 offset:2048
	ds_read_b32 v66, v47 offset:2304
	ds_read_b128 v[34:37], v46 offset:2816
	ds_read_b128 v[12:15], v46 offset:1536
	v_pk_mul_f32 v[94:95], v[94:95], v[44:45]
	s_add_i32 s21, s21, 1
	v_pk_fma_f32 v[92:93], v[92:93], v[42:43], v[94:95]
	s_nop 0
	v_add_f32_e32 v92, v92, v93
	ds_write_b32 v51, v92 offset:768
	s_cmpk_lg_u32 s21, 0x200
	s_cbranch_scc1 .LBB0_707
	s_branch .LBB0_704

; #define LAS __attribute__((address_space(3)))
; #define GAS __attribute__((address_space(1)))
; __device__ __forceinline__ void rwkv_prompt_wave4(LAS float* ring, const GAS float* RW, int mbase, int h, int rq, GAS float* Sout, GAS float* YR, int lane) {
;     const int rl = lane >> 4, cgp = lane & 15;
;     f32x2 S[2] = {{0.f, 0.f}, {0.f, 0.f}};
;     unsigned off[6];
; #pragma unroll
;     for (int i = 0; i < 6; ++i) { const int e = i * 256 + lane * 4, st = e / 384, rem = e - st * 384; off[i] = (unsigned)((rem >> 6) * SZ + st * 512 + (rem & 63)); }
;     const GAS float* gp = RW + (size_t)mbase * 512 + h * 64;
;     constexpr int NCH = SEQ / 4;
;     ...
;         if (cgp < 4) YR[(size_t)(mbase + ci * 4 + cgp) * 512 + h * 64 + rq * 4 + rl] = ykeep;
.Lld_restart:
	s_and_b32 s23, s0, 3
	s_lshl_b32 s23, s23, 2
	s_or_b32 s23, s23, s1
	s_lshl_b32 s23, s23, 4
	s_add_u32 s98, s4, 0x8800000
	s_addc_u32 s99, s5, 0
	s_add_u32 s98, s98, s23
	s_addc_u32 s99, s99, 0
	s_lshl_b32 s25, s1, 13
	s_add_i32 s25, s25, 0x18000
	v_and_b32_e32 v22, 63, v195
	v_and_b32_e32 v23, 15, v22
	v_lshrrev_b32_e32 v24, 4, v22
	v_lshl_add_u32 v25, v22, 2, s25
	v_lshlrev_b32_e32 v27, 11, v23
	v_lshl_add_u32 v27, v24, 2, v27
	v_cmp_eq_u32_e64 s[30:31], 0, v23
	v_cmp_eq_u32_e64 s[32:33], 2, v23
	v_cmp_eq_u32_e64 s[44:45], 3, v23
	v_cmp_gt_u32_e64 s[62:63], 4, v23
	s_mov_b32 s22, 0
	s_mov_b32 s14, 0
	s_mov_b32 s17, 0
	s_mov_b32 s18, 0

; #define LAS __attribute__((address_space(3)))
; #define R4_ISSUE(cc, slot) do { const GAS float* g_ = gp + (size_t)(cc) * 2048; LAS float* l_ = ring + (slot) * 1536; _Pragma("unroll") for (int i_ = 0; i_ < 6; ++i_) \
;         __builtin_amdgcn_global_load_lds((const GAS unsigned*)(g_ + off[i_]), (LAS unsigned*)(l_ + i_ * 256), 16, 0, 0); } while (0)
; #define R4_LOAD(o, sb_) do { const LAS float* sb = (sb_); (o).r = *(const LAS f32x4*)(sb + cgp * 4); (o).w = *(const LAS f32x4*)(sb + 64 + cgp * 4); (o).k = *(const LAS f32x4*)(sb + 128 + cgp * 4); \
;         (o).a = *(const LAS f32x4*)(sb + 256 + cgp * 4); (o).b = *(const LAS f32x4*)(sb + 320 + cgp * 4); (o).vv = sb[192 + rq * 4 + rl]; asm volatile("" ::: "memory"); } while (0)
; __device__ __forceinline__ void rwkv_prompt_wave4(LAS float* ring, const GAS float* RW, int mbase, int h, int rq, GAS float* Sout, GAS float* YR, int lane) {
;     ...
;     for (int cc = 0; cc < 3; ++cc) R4_ISSUE(cc, cc);
;     float ykeep = 0.f;
;     R4Ops oA, oB, oC, oD;
;     asm volatile("s_waitcnt vmcnt(12)" ::: "memory");
;     R4_LOAD(oA, ring); R4_LOAD(oB, ring + 384);
;     for (int ci = 0; ci < NCH; ++ci) {
;         { const int cn = ci + 3; const int cl = cn < NCH ? cn : NCH - 1; R4_ISSUE(cl, cn % R4_NS); }
;         const LAS float* cb = ring + (ci % R4_NS) * 1536; const LAS float* nb = ring + ((ci + 1) % R4_NS) * 1536;
;         R4_LOAD(oC, cb + 768);  R4_STEP(oA, 0);
;         R4_LOAD(oD, cb + 1152); R4_STEP(oB, 1);
;         asm volatile("s_waitcnt vmcnt(12)" ::: "memory");
.Lld_loop:
	s_cmp_eq_u32 s18, 0x80
	s_cbranch_scc1 .Lld_bar
	s_cmp_ge_u32 s1, 2
	s_cbranch_scc1 .Lld_w1
	s_cmp_lt_u32 s18, 2
	s_cbranch_scc1 .Lld_w0a
	s_cmp_eq_u32 s18, 2
	s_cbranch_scc1 .Lld_w0b
	s_waitcnt vmcnt(22)
	s_branch .Lld_bar
.Lld_w0a:
	s_waitcnt vmcnt(14)
	s_branch .Lld_bar
.Lld_w0b:
	s_waitcnt vmcnt(18)
	s_branch .Lld_bar
.Lld_w1:
	s_cmp_lt_u32 s18, 2
	s_cbranch_scc1 .Lld_w1a
	s_cmp_eq_u32 s18, 2
	s_cbranch_scc1 .Lld_w1b
	s_waitcnt vmcnt(15)
	s_branch .Lld_bar
.Lld_w1a:
	s_waitcnt vmcnt(7)
	s_branch .Lld_bar

; #define LAS __attribute__((address_space(3)))
; #define R4_ISSUE(cc, slot) do { const GAS float* g_ = gp + (size_t)(cc) * 2048; LAS float* l_ = ring + (slot) * 1536; _Pragma("unroll") for (int i_ = 0; i_ < 6; ++i_) \
;         __builtin_amdgcn_global_load_lds((const GAS unsigned*)(g_ + off[i_]), (LAS unsigned*)(l_ + i_ * 256), 16, 0, 0); } while (0)
; #define R4_LOAD(o, sb_) do { const LAS float* sb = (sb_); (o).r = *(const LAS f32x4*)(sb + cgp * 4); (o).w = *(const LAS f32x4*)(sb + 64 + cgp * 4); (o).k = *(const LAS f32x4*)(sb + 128 + cgp * 4); \
;         (o).a = *(const LAS f32x4*)(sb + 256 + cgp * 4); (o).b = *(const LAS f32x4*)(sb + 320 + cgp * 4); (o).vv = sb[192 + rq * 4 + rl]; asm volatile("" ::: "memory"); } while (0)
; __device__ __forceinline__ void rwkv_prompt_wave4(LAS float* ring, const GAS float* RW, int mbase, int h, int rq, GAS float* Sout, GAS float* YR, int lane) {
;     ...
;     for (int cc = 0; cc < 3; ++cc) R4_ISSUE(cc, cc);
;     float ykeep = 0.f;
;     R4Ops oA, oB, oC, oD;
;     asm volatile("s_waitcnt vmcnt(12)" ::: "memory");
;     R4_LOAD(oA, ring); R4_LOAD(oB, ring + 384);
;     for (int ci = 0; ci < NCH; ++ci) {
;         { const int cn = ci + 3; const int cl = cn < NCH ? cn : NCH - 1; R4_ISSUE(cl, cn % R4_NS); }
;         const LAS float* cb = ring + (ci % R4_NS) * 1536; const LAS float* nb = ring + ((ci + 1) % R4_NS) * 1536;
;         R4_LOAD(oC, cb + 768);  R4_STEP(oA, 0);
;         R4_LOAD(oD, cb + 1152); R4_STEP(oB, 1);
;         asm volatile("s_waitcnt vmcnt(12)" ::: "memory");
;         R4_LOAD(oA, nb);        R4_STEP(oC, 2);
;         R4_LOAD(oB, nb + 384);  R4_STEP(oD, 3);
;         if (cgp < 4) YR[(size_t)(mbase + ci * 4 + cgp) * 512 + h * 64 + rq * 4 + rl] = ykeep;
.Lld_bar:
	s_barrier
	s_cmp_eq_u32 s18, 0x80
	s_cbranch_scc1 .Lld_y
	s_mov_b32 s19, 4
	s_branch .Lld_issue
.Lld_next:
	s_sub_u32 s19, s19, 1
	s_cmp_lg_u32 s19, 0
	s_cbranch_scc1 .Lld_issue
	s_cmp_eq_u32 s18, 0
	s_cbranch_scc1 .Lld_ynone
.Lld_y:
	s_mov_b32 s19, 4
.Lld_ychunk:
	v_add_u32_e32 v28, s22, v25
	ds_read_b32 v32, v28
	ds_read_b32 v33, v28 offset:256
	ds_read_b32 v34, v28 offset:512
	ds_read_b32 v35, v28 offset:768
	s_add_i32 s22, s22, 0x400
	s_and_b32 s22, s22, 0x1fff
	s_waitcnt lgkmcnt(0)
	v_add_f32_dpp v32, v32, v32 quad_perm:[1,0,3,2] row_mask:0xf bank_mask:0xf bound_ctrl:1
	v_add_f32_dpp v33, v33, v33 quad_perm:[1,0,3,2] row_mask:0xf bank_mask:0xf bound_ctrl:1
	v_add_f32_dpp v34, v34, v34 quad_perm:[1,0,3,2] row_mask:0xf bank_mask:0xf bound_ctrl:1
	v_add_f32_dpp v35, v35, v35 quad_perm:[1,0,3,2] row_mask:0xf bank_mask:0xf bound_ctrl:1
	v_add_f32_dpp v32, v32, v32 quad_perm:[2,3,0,1] row_mask:0xf bank_mask:0xf bound_ctrl:1
	v_add_f32_dpp v33, v33, v33 quad_perm:[2,3,0,1] row_mask:0xf bank_mask:0xf bound_ctrl:1
	v_add_f32_dpp v34, v34, v34 quad_perm:[2,3,0,1] row_mask:0xf bank_mask:0xf bound_ctrl:1
	v_add_f32_dpp v35, v35, v35 quad_perm:[2,3,0,1] row_mask:0xf bank_mask:0xf bound_ctrl:1
	v_add_f32_dpp v32, v32, v32 row_half_mirror row_mask:0xf bank_mask:0xf bound_ctrl:1
	v_add_f32_dpp v33, v33, v33 row_half_mirror row_mask:0xf bank_mask:0xf bound_ctrl:1
	v_add_f32_dpp v34, v34, v34 row_half_mirror row_mask:0xf bank_mask:0xf bound_ctrl:1
	v_add_f32_dpp v35, v35, v35 row_half_mirror row_mask:0xf bank_mask:0xf bound_ctrl:1
	v_add_f32_dpp v32, v32, v32 row_mirror row_mask:0xf bank_mask:0xf bound_ctrl:1
	v_add_f32_dpp v33, v33, v33 row_mirror row_mask:0xf bank_mask:0xf bound_ctrl:1
	v_add_f32_dpp v34, v34, v34 row_mirror row_mask:0xf bank_mask:0xf bound_ctrl:1
	v_add_f32_dpp v35, v35, v35 row_mirror row_mask:0xf bank_mask:0xf bound_ctrl:1
	v_cndmask_b32_e64 v36, v33, v32, s[30:31]
	v_cndmask_b32_e64 v36, v36, v34, s[32:33]
	v_cndmask_b32_e64 v36, v36, v35, s[44:45]
	s_mov_b64 exec, s[62:63]
	global_store_dword v27, v36, s[98:99]
	s_mov_b64 exec, -1
	s_add_u32 s98, s98, 0x2000
	s_addc_u32 s99, s99, 0
	s_sub_u32 s19, s19, 1
	s_cmp_lg_u32 s19, 0
	s_cbranch_scc1 .Lld_ychunk
.Lld_ynone:
	s_add_u32 s18, s18, 1
	s_cmp_le_u32 s18, 0x80
	s_cbranch_scc1 .Lld_loop
	s_waitcnt vmcnt(0)
